# seam between FFN-down0 and the fix-up phase without its L2 write-back (split-K partials stored write-through instead)
# speedup vs baseline: 1.0062x; 1.0062x over previous
; __device__ __forceinline__ unsigned xb_add(unsigned* p, unsigned v) { return __hip_atomic_fetch_add(p, v, __ATOMIC_RELAXED, __HIP_MEMORY_SCOPE_AGENT); }
; __device__ __forceinline__ void xcd_barrier(const XcdBarrier& b) {
;     ...
;         if (old + 1u == (gen + 1u) * nloc) {
;             __builtin_amdgcn_fence(__ATOMIC_RELEASE, "agent");
;             asm volatile("s_waitcnt vmcnt(0)" ::: "memory");
;             const unsigned og = xb_add(&bar[XB_TOP], 1u);
.LBB0_651:
	s_andn2_saveexec_b64 s[6:7], s[6:7]
	s_cbranch_execz .LBB0_671
	s_mov_b64 s[6:7], exec
	buffer_inv sc1
	s_nop 0
	s_waitcnt lgkmcnt(0)
	s_waitcnt vmcnt(0)
	v_mbcnt_lo_u32_b32 v1, s6, 0
	v_mbcnt_hi_u32_b32 v1, s7, v1
	v_cmp_eq_u32_e32 vcc, 0, v1
	s_and_saveexec_b64 s[12:13], vcc
	s_cbranch_execz .LBB0_654
	s_bcnt1_i32_b64 s6, s[6:7]
	v_mov_b32_e32 v2, 0x83000
	v_mov_b32_e32 v3, s6
	global_atomic_add v2, v2, v3, s[72:73] offset:1024 sc0
